# idle workgroups prefetch the resid tail half-tiles' A/B lines into their XCD's L2 (one dword per 128B line, K-step order)
# baseline (speedup 1.0000x reference)
; template <int NT>
; __device__ __forceinline__ void gemm_tile(f32x4 (&acc)[4][NT], const bf16_t* A, int lda, const bf16_t* B, int ldb, int K, bf16_t* sm) {
;     ...
;     for (int kt = 0; kt < nk; ++kt) {
;         lds_barrier();
; #pragma unroll
;         for (int i = 0; i < 4; ++i) *(u32x4*)(sA + (lrow + 32 * i) * LDT + lkc * 8) = ra0[i];
; #pragma unroll
;         for (int i = 0; i < NT; ++i) *(u32x4*)(sB + sbrow[i] * LDT + lkc * 8) = rb0[i];
;         lds_barrier();
;         if (kt + 1 < nk) {
;             ga += 64; gb += 64;
; #pragma unroll
;             for (int i = 0; i < 4; ++i) ra0[i] = *(const u32x4*)(ga + (size_t)(32 * i) * lda);
; #pragma unroll
;             for (int i = 0; i < NT; ++i) rb0[i] = *(const u32x4*)(gb + (size_t)(32 * i) * ldb);
;         }
;         __builtin_amdgcn_sched_barrier(0);
;         gemm_compute<NT>(acc, sA, sB, wr, wc, fr, fq);
;         __builtin_amdgcn_sched_barrier(0);
;     }
; template <int NT>
; __device__ __forceinline__ void resid_tile(int tm, int col0, const bf16_t* A, int lda, int K, const bf16_t* W, const float* X, float* Y, float scale, bf16_t* sm) {
;     ...
; #pragma unroll
;     for (int mt = 0; mt < 4; ++mt) {
;         const int row = tm * 128 + wr * 64 + mt * 16 + fr;
;         const int cbase = col0 + wc * 16 * NT + fq * 4 * NT;
;         const size_t o = (size_t)row * 1024 + cbase;
;         float v[4 * NT]; gather_cols<NT>(acc, mt, v);
;         float4 xv[NT];
; #pragma unroll
;         for (int q = 0; q < NT; ++q) xv[q] = *(const float4*)(X + o + 4 * q);
; #pragma unroll
;         for (int q = 0; q < NT; ++q)
;             *(float4*)(Y + o + 4 * q) = make_float4(ALPHA * xv[q].x + scale * v[4 * q], ALPHA * xv[q].y + scale * v[4 * q + 1],
;                                                     ALPHA * xv[q].z + scale * v[4 * q + 2], ALPHA * xv[q].w + scale * v[4 * q + 3]);
.LBB0_41:
	s_waitcnt lgkmcnt(0)
	s_barrier
	s_waitcnt vmcnt(3)
	ds_write_b128 v74, v[18:21]
	s_waitcnt vmcnt(2)
	ds_write_b128 v74, v[8:11] offset:5120
	s_waitcnt vmcnt(1)
	ds_write_b128 v74, v[14:17] offset:10240
	s_waitcnt vmcnt(0)
	ds_write_b128 v74, v[22:25] offset:15360
	ds_write_b128 v75, v[4:7] offset:20480
	ds_write_b128 v76, v[0:3] offset:20480
	s_waitcnt lgkmcnt(0)
	s_barrier
	v_lshl_add_u64 v[0:1], v[66:67], 0, v[58:59]
	global_load_dwordx4 v[18:21], v[0:1], off
	v_lshl_add_u64 v[0:1], v[64:65], 0, v[58:59]
	global_load_dwordx4 v[8:11], v[0:1], off
	v_lshl_add_u64 v[0:1], v[62:63], 0, v[58:59]
	global_load_dwordx4 v[14:17], v[0:1], off
	v_lshl_add_u64 v[0:1], v[60:61], 0, v[58:59]
	global_load_dwordx4 v[22:25], v[0:1], off
	v_lshl_add_u64 v[0:1], v[70:71], 0, v[58:59]
	global_load_dwordx4 v[4:7], v[0:1], off
	v_lshl_add_u64 v[0:1], v[68:69], 0, v[58:59]
	global_load_dwordx4 v[0:3], v[0:1], off
	ds_read_b128 v[78:81], v73
	ds_read_b128 v[82:85], v73 offset:2560
	ds_read_b128 v[86:89], v73 offset:5120
	ds_read_b128 v[90:93], v73 offset:7680
	ds_read_b128 v[94:97], v12 offset:20480
	ds_read_b128 v[100:103], v12 offset:23040
	s_setprio 1
	s_waitcnt lgkmcnt(1)
	v_mfma_f32_16x16x32_bf16 v[26:29], v[94:97], v[78:81], v[26:29]
	s_waitcnt lgkmcnt(0)
	v_mfma_f32_16x16x32_bf16 v[54:57], v[100:103], v[78:81], v[54:57]
	v_mfma_f32_16x16x32_bf16 v[50:53], v[94:97], v[82:85], v[50:53]
	v_mfma_f32_16x16x32_bf16 v[46:49], v[100:103], v[82:85], v[46:49]
	v_mfma_f32_16x16x32_bf16 v[42:45], v[94:97], v[86:89], v[42:45]
	v_mfma_f32_16x16x32_bf16 v[38:41], v[100:103], v[86:89], v[38:41]
	v_mfma_f32_16x16x32_bf16 v[34:37], v[94:97], v[90:93], v[34:37]
	v_mfma_f32_16x16x32_bf16 v[30:33], v[100:103], v[90:93], v[30:33]
	s_setprio 0
	ds_read_b128 v[78:81], v73 offset:64
	ds_read_b128 v[82:85], v73 offset:2624
	ds_read_b128 v[86:89], v73 offset:5184
	ds_read_b128 v[90:93], v73 offset:7744
	ds_read_b128 v[94:97], v12 offset:20544
	ds_read_b128 v[100:103], v12 offset:23104
	s_setprio 1
	s_waitcnt lgkmcnt(1)
	v_mfma_f32_16x16x32_bf16 v[26:29], v[94:97], v[78:81], v[26:29]
	s_waitcnt lgkmcnt(0)
	v_mfma_f32_16x16x32_bf16 v[54:57], v[100:103], v[78:81], v[54:57]
	v_mfma_f32_16x16x32_bf16 v[50:53], v[94:97], v[82:85], v[50:53]
	v_mfma_f32_16x16x32_bf16 v[46:49], v[100:103], v[82:85], v[46:49]
	v_mfma_f32_16x16x32_bf16 v[42:45], v[94:97], v[86:89], v[42:45]
	v_mfma_f32_16x16x32_bf16 v[38:41], v[100:103], v[86:89], v[38:41]
	v_mfma_f32_16x16x32_bf16 v[34:37], v[94:97], v[90:93], v[34:37]
	v_mfma_f32_16x16x32_bf16 v[30:33], v[100:103], v[90:93], v[30:33]
	s_setprio 0
	s_add_i32 s49, s49, -1
	v_lshl_add_u64 v[60:61], v[60:61], 0, s[4:5]
	v_lshl_add_u64 v[62:63], v[62:63], 0, s[4:5]
	v_lshl_add_u64 v[64:65], v[64:65], 0, s[4:5]
	v_lshl_add_u64 v[66:67], v[66:67], 0, s[4:5]
	v_lshl_add_u64 v[68:69], v[68:69], 0, s[4:5]
	s_cmp_lg_u32 s49, 0
	v_lshl_add_u64 v[70:71], v[70:71], 0, s[4:5]
	s_cbranch_scc1 .LBB0_41
	s_waitcnt lgkmcnt(0)
	s_barrier
	s_waitcnt vmcnt(5)
	ds_write_b128 v74, v[18:21]
	s_waitcnt vmcnt(4)
	ds_write_b128 v74, v[8:11] offset:5120
	s_waitcnt vmcnt(3)
	ds_write_b128 v74, v[14:17] offset:10240
	s_waitcnt vmcnt(2)
	ds_write_b128 v74, v[22:25] offset:15360
	s_waitcnt vmcnt(1)
	ds_write_b128 v75, v[4:7] offset:20480
	s_waitcnt vmcnt(0)
	ds_write_b128 v76, v[0:3] offset:20480
	s_waitcnt lgkmcnt(0)
	s_barrier
	ds_read_b128 v[0:3], v73
	ds_read_b128 v[4:7], v73 offset:2560
	ds_read_b128 v[8:11], v73 offset:5120
	ds_read_b128 v[14:17], v73 offset:7680
	ds_read_b128 v[18:21], v12 offset:20480
	ds_read_b128 v[22:25], v12 offset:23040
	s_setprio 1
	s_waitcnt lgkmcnt(1)
	v_mfma_f32_16x16x32_bf16 v[26:29], v[18:21], v[0:3], v[26:29]
	s_waitcnt lgkmcnt(0)
	v_mfma_f32_16x16x32_bf16 v[0:3], v[22:25], v[0:3], v[54:57]
	v_mfma_f32_16x16x32_bf16 v[50:53], v[18:21], v[4:7], v[50:53]
	v_mfma_f32_16x16x32_bf16 v[4:7], v[22:25], v[4:7], v[46:49]
	v_mfma_f32_16x16x32_bf16 v[42:45], v[18:21], v[8:11], v[42:45]
	v_mfma_f32_16x16x32_bf16 v[38:41], v[22:25], v[8:11], v[38:41]
	v_mfma_f32_16x16x32_bf16 v[18:21], v[18:21], v[14:17], v[34:37]
	v_mfma_f32_16x16x32_bf16 v[22:25], v[22:25], v[14:17], v[30:33]
	s_setprio 0
	ds_read_b128 v[8:11], v73 offset:64
	ds_read_b128 v[14:17], v73 offset:2624
	ds_read_b128 v[30:33], v73 offset:5184
	ds_read_b128 v[34:37], v73 offset:7744
	ds_read_b128 v[46:49], v12 offset:20544
	ds_read_b128 v[54:57], v12 offset:23104
	s_setprio 1
	s_waitcnt lgkmcnt(1)
	v_mfma_f32_16x16x32_bf16 v[26:29], v[46:49], v[8:11], v[26:29]
	s_waitcnt lgkmcnt(0)
	v_mfma_f32_16x16x32_bf16 v[58:61], v[54:57], v[8:11], v[0:3]
	v_mfma_f32_16x16x32_bf16 v[50:53], v[46:49], v[14:17], v[50:53]
	v_mfma_f32_16x16x32_bf16 v[62:65], v[54:57], v[14:17], v[4:7]
	v_mfma_f32_16x16x32_bf16 v[8:11], v[46:49], v[30:33], v[42:45]
	v_mfma_f32_16x16x32_bf16 v[14:17], v[54:57], v[30:33], v[38:41]
	v_mfma_f32_16x16x32_bf16 v[0:3], v[46:49], v[34:37], v[18:21]
	v_mfma_f32_16x16x32_bf16 v[4:7], v[54:57], v[34:37], v[22:25]
	s_setprio 0
	v_ashrrev_i32_e32 v12, 1, v72
	v_and_b32_e32 v12, 0xffffffc0, v12
	v_lshl_add_u32 v12, s52, 7, v12
	v_and_or_b32 v18, v72, 15, v12
	v_lshrrev_b32_e32 v12, 1, v72
	v_and_or_b32 v12, v12, 56, s2
	v_ashrrev_i32_e32 v19, 31, v18
	v_lshlrev_b64 v[20:21], 12, v[18:19]
	v_lshlrev_b32_e32 v12, 2, v12
	v_or_b32_e32 v20, v20, v12
	v_lshl_add_u64 v[24:25], s[56:57], 0, v[20:21]
	v_lshl_add_u64 v[34:35], s[90:91], 0, v[20:21]
	global_load_dwordx4 v[20:23], v[24:25], off offset:16
	global_load_dwordx4 v[30:33], v[24:25], off
	s_add_i32 s78, s78, s62
	s_cmp_ge_i32 s78, s79
	s_waitcnt vmcnt(1)
	v_pk_mul_f32 v[20:21], v[20:21], s[88:89] op_sel_hi:[1,0]
	s_waitcnt vmcnt(0)
; template <int NT>
; __device__ __forceinline__ void resid_tile(int tm, int col0, const bf16_t* A, int lda, int K, const bf16_t* W, const float* X, float* Y, float scale, bf16_t* sm) {
;     ...
;     for (int mt = 0; mt < 4; ++mt) {
;         const int row = tm * 128 + wr * 64 + mt * 16 + fr;
;         const int cbase = col0 + wc * 16 * NT + fq * 4 * NT;
;         const size_t o = (size_t)row * 1024 + cbase;
;         float v[4 * NT]; gather_cols<NT>(acc, mt, v);
;         float4 xv[NT];
; #pragma unroll
;         for (int q = 0; q < NT; ++q) xv[q] = *(const float4*)(X + o + 4 * q);
; #pragma unroll
;         for (int q = 0; q < NT; ++q)
;             *(float4*)(Y + o + 4 * q) = make_float4(ALPHA * xv[q].x + scale * v[4 * q], ALPHA * xv[q].y + scale * v[4 * q + 1],
;                                                     ALPHA * xv[q].z + scale * v[4 * q + 2], ALPHA * xv[q].w + scale * v[4 * q + 3]);
;     }
; }
; __device__ __forceinline__ void phase_gemm_resid(const bf16_t* A, int lda, int K, const bf16_t* W, const float* X, float* Y, float scale, bf16_t* sm) {
;     const int G = gridDim.x, NTILES = 136 * 8;
;     const int nfull = (NTILES / G) * G;
;     for (int t = blockIdx.x; t < nfull; t += G) resid_tile<4>(t >> 3, (t & 7) * 128, A, lda, K, W, X, Y, scale, sm);
;     for (int u = blockIdx.x; u < 2 * (NTILES - nfull); u += G) {
;         const int t = nfull + (u >> 1);
;         resid_tile<2>(t >> 3, (t & 7) * 128 + (u & 1) * 64, A, lda, K, W, X, Y, scale, sm);
;     }
	v_pk_mul_f32 v[24:25], v[30:31], s[88:89] op_sel_hi:[1,0]
	v_mov_b32_e32 v30, v26
	v_mov_b32_e32 v31, v58
	v_pk_fma_f32 v[24:25], v[98:99], v[30:31], v[24:25]
	v_pk_mul_f32 v[30:31], v[32:33], s[88:89] op_sel_hi:[1,0]
	v_mov_b32_e32 v58, v27
	v_pk_fma_f32 v[26:27], v[98:99], v[58:59], v[30:31]
	v_mov_b32_e32 v30, v28
	v_mov_b32_e32 v31, v60
	v_pk_fma_f32 v[20:21], v[98:99], v[30:31], v[20:21]
	v_pk_mul_f32 v[22:23], v[22:23], s[88:89] op_sel_hi:[1,0]
	v_mov_b32_e32 v60, v29
	v_pk_fma_f32 v[22:23], v[98:99], v[60:61], v[22:23]
	global_store_dwordx4 v[34:35], v[24:27], off
	global_store_dwordx4 v[34:35], v[20:23], off offset:16
	v_mov_b32_e32 v30, v50
	v_mov_b32_e32 v31, v62
	v_or_b32_e32 v20, 16, v18
	v_ashrrev_i32_e32 v21, 31, v20
	v_lshlrev_b64 v[20:21], 12, v[20:21]
	v_or_b32_e32 v20, v20, v12
	v_lshl_add_u64 v[24:25], s[56:57], 0, v[20:21]
	v_lshl_add_u64 v[28:29], s[90:91], 0, v[20:21]
	global_load_dwordx4 v[20:23], v[24:25], off offset:16
	s_nop 0
	global_load_dwordx4 v[24:27], v[24:25], off
	v_mov_b32_e32 v62, v51
	s_waitcnt vmcnt(1)
	v_pk_mul_f32 v[20:21], v[20:21], s[88:89] op_sel_hi:[1,0]
	s_waitcnt vmcnt(0)
	v_pk_mul_f32 v[24:25], v[24:25], s[88:89] op_sel_hi:[1,0]
	v_pk_mul_f32 v[26:27], v[26:27], s[88:89] op_sel_hi:[1,0]
	v_pk_fma_f32 v[24:25], v[98:99], v[30:31], v[24:25]
	v_mov_b32_e32 v30, v52
	v_mov_b32_e32 v31, v64
	v_pk_fma_f32 v[26:27], v[98:99], v[62:63], v[26:27]
	v_pk_fma_f32 v[20:21], v[98:99], v[30:31], v[20:21]
	v_pk_mul_f32 v[22:23], v[22:23], s[88:89] op_sel_hi:[1,0]
	v_mov_b32_e32 v64, v53
	v_pk_fma_f32 v[22:23], v[98:99], v[64:65], v[22:23]
	global_store_dwordx4 v[28:29], v[24:27], off
	global_store_dwordx4 v[28:29], v[20:23], off offset:16
	v_mov_b32_e32 v31, v14
	v_mov_b32_e32 v14, v9
	v_or_b32_e32 v20, 32, v18
	v_ashrrev_i32_e32 v21, 31, v20
	v_lshlrev_b64 v[20:21], 12, v[20:21]
	v_or_b32_e32 v20, v20, v12
	v_lshl_add_u64 v[24:25], s[56:57], 0, v[20:21]
	v_lshl_add_u64 v[28:29], s[90:91], 0, v[20:21]
	global_load_dwordx4 v[20:23], v[24:25], off offset:16
	s_nop 0
	global_load_dwordx4 v[24:27], v[24:25], off
	v_mov_b32_e32 v30, v8
	s_waitcnt vmcnt(1)
	v_pk_mul_f32 v[8:9], v[20:21], s[88:89] op_sel_hi:[1,0]
	s_waitcnt vmcnt(0)
	v_pk_mul_f32 v[26:27], v[26:27], s[88:89] op_sel_hi:[1,0]
	v_pk_mul_f32 v[24:25], v[24:25], s[88:89] op_sel_hi:[1,0]
	v_pk_fma_f32 v[26:27], v[98:99], v[14:15], v[26:27]
	v_mov_b32_e32 v14, v10
	v_mov_b32_e32 v15, v16
	v_pk_fma_f32 v[24:25], v[98:99], v[30:31], v[24:25]
	v_pk_fma_f32 v[8:9], v[98:99], v[14:15], v[8:9]
	v_pk_mul_f32 v[14:15], v[22:23], s[88:89] op_sel_hi:[1,0]
	v_mov_b32_e32 v16, v11
	v_pk_fma_f32 v[10:11], v[98:99], v[16:17], v[14:15]
	global_store_dwordx4 v[28:29], v[24:27], off
	global_store_dwordx4 v[28:29], v[8:11], off offset:16
	v_mov_b32_e32 v21, v4
	v_mov_b32_e32 v4, v1
	v_or_b32_e32 v8, 48, v18
	v_ashrrev_i32_e32 v9, 31, v8
	v_lshlrev_b64 v[8:9], 12, v[8:9]
	v_or_b32_e32 v8, v8, v12
	v_lshl_add_u64 v[14:15], s[56:57], 0, v[8:9]
	v_lshl_add_u64 v[18:19], s[90:91], 0, v[8:9]
	global_load_dwordx4 v[8:11], v[14:15], off offset:16
	s_nop 0
	global_load_dwordx4 v[14:17], v[14:15], off
	v_mov_b32_e32 v20, v0
	s_waitcnt vmcnt(1)
	v_pk_mul_f32 v[0:1], v[8:9], s[88:89] op_sel_hi:[1,0]
	s_waitcnt vmcnt(0)
	v_pk_mul_f32 v[16:17], v[16:17], s[88:89] op_sel_hi:[1,0]
	v_pk_mul_f32 v[14:15], v[14:15], s[88:89] op_sel_hi:[1,0]
	v_pk_fma_f32 v[16:17], v[98:99], v[4:5], v[16:17]
	v_mov_b32_e32 v4, v2
	v_mov_b32_e32 v5, v6
	v_pk_fma_f32 v[14:15], v[98:99], v[20:21], v[14:15]
	v_pk_fma_f32 v[0:1], v[98:99], v[4:5], v[0:1]
	v_pk_mul_f32 v[4:5], v[10:11], s[88:89] op_sel_hi:[1,0]
	v_mov_b32_e32 v6, v3
	v_pk_fma_f32 v[2:3], v[98:99], v[6:7], v[4:5]
	global_store_dwordx4 v[18:19], v[14:17], off
	global_store_dwordx4 v[18:19], v[0:3], off offset:16
	s_cbranch_scc0 .LBB0_40
	s_branch .LBB0_43
.Lpf_resid:
	v_readlane_b32 s74, v231, 56
	s_and_b32 s75, s74, 7
	s_add_i32 s74, s74, 0xffffff80
	s_lshr_b32 s74, s74, 3
	s_lshl_b32 s74, s74, 8
	v_add_u32_e32 v236, s74, v192
	s_lshl_b32 s76, s96, 15
	s_add_u32 s76, s12, s76
	s_addc_u32 s77, s11, 0
	s_mov_b32 s78, s13
	s_mov_b32 s79, s94
	s_mul_i32 s18, s96, 18
	s_lshr_b32 s19, s75, 1
	s_lshl_b32 s19, s19, 7
	s_and_b32 s75, s75, 1
	s_lshl_b32 s75, s75, 6
	s_add_i32 s19, s19, s75
	v_mov_b32_e32 v246, s76
	v_mov_b32_e32 v247, s77
	v_mov_b32_e32 v248, s78
	v_mov_b32_e32 v249, s79
	s_mov_b32 s74, 0xe38f
	v_mul_lo_u32 v237, v236, s74
	v_lshrrev_b32_e32 v237, 26, v237
	v_mul_u32_u24_e32 v238, 0x480, v237
	v_sub_u32_e32 v238, v236, v238
	v_add_u32_e32 v239, 0xfffffc00, v238
	v_and_b32_e32 v240, 63, v239
	v_lshrrev_b32_e32 v241, 6, v239
	v_lshl_add_u32 v240, v241, 9, v240
	v_add_u32_e32 v240, s19, v240
	v_cmp_lt_u32_e32 vcc, 0x3ff, v238
	s_nop 1
	v_cndmask_b32_e32 v240, v238, v240, vcc
	v_cndmask_b32_e32 v242, v246, v248, vcc
	v_cndmask_b32_e32 v243, v247, v249, vcc
	v_mul_lo_u32 v240, v240, s96
	v_lshlrev_b32_e32 v240, 1, v240
	v_lshl_add_u32 v240, v237, 7, v240
	v_cmp_gt_u32_e32 vcc, s18, v236
	s_nop 1
	v_cndmask_b32_e32 v240, 0, v240, vcc
	v_cndmask_b32_e32 v242, v246, v242, vcc
	v_cndmask_b32_e32 v243, v247, v243, vcc
	v_mov_b32_e32 v241, 0
	v_lshl_add_u64 v[242:243], v[242:243], 0, v[240:241]
	global_load_dword v250, v[242:243], off
	v_add_u32_e32 v236, 0x3000, v236
	v_mul_lo_u32 v237, v236, s74
	v_lshrrev_b32_e32 v237, 26, v237
	v_mul_u32_u24_e32 v238, 0x480, v237
	v_sub_u32_e32 v238, v236, v238
	v_add_u32_e32 v239, 0xfffffc00, v238
	v_and_b32_e32 v240, 63, v239
	v_lshrrev_b32_e32 v241, 6, v239
	v_lshl_add_u32 v240, v241, 9, v240
	v_add_u32_e32 v240, s19, v240
	v_cmp_lt_u32_e32 vcc, 0x3ff, v238
	s_nop 1
	v_cndmask_b32_e32 v240, v238, v240, vcc
	v_cndmask_b32_e32 v242, v246, v248, vcc
	v_cndmask_b32_e32 v243, v247, v249, vcc
	v_mul_lo_u32 v240, v240, s96
	v_lshlrev_b32_e32 v240, 1, v240
	v_lshl_add_u32 v240, v237, 7, v240
	v_cmp_gt_u32_e32 vcc, s18, v236
	s_nop 1
	v_cndmask_b32_e32 v240, 0, v240, vcc
	v_cndmask_b32_e32 v242, v246, v242, vcc
	v_cndmask_b32_e32 v243, v247, v243, vcc
	v_mov_b32_e32 v241, 0
	v_lshl_add_u64 v[242:243], v[242:243], 0, v[240:241]
	global_load_dword v251, v[242:243], off
	v_add_u32_e32 v236, 0x3000, v236
	v_mul_lo_u32 v237, v236, s74
	v_lshrrev_b32_e32 v237, 26, v237
	v_mul_u32_u24_e32 v238, 0x480, v237
	v_sub_u32_e32 v238, v236, v238
	v_add_u32_e32 v239, 0xfffffc00, v238
	v_and_b32_e32 v240, 63, v239
	v_lshrrev_b32_e32 v241, 6, v239
	v_lshl_add_u32 v240, v241, 9, v240
	v_add_u32_e32 v240, s19, v240
	v_cmp_lt_u32_e32 vcc, 0x3ff, v238
	s_nop 1
	v_cndmask_b32_e32 v240, v238, v240, vcc
	v_cndmask_b32_e32 v242, v246, v248, vcc
	v_cndmask_b32_e32 v243, v247, v249, vcc
	v_mul_lo_u32 v240, v240, s96
	v_lshlrev_b32_e32 v240, 1, v240
	v_lshl_add_u32 v240, v237, 7, v240
	v_cmp_gt_u32_e32 vcc, s18, v236
	s_nop 1
	v_cndmask_b32_e32 v240, 0, v240, vcc
	v_cndmask_b32_e32 v242, v246, v242, vcc
	v_cndmask_b32_e32 v243, v247, v243, vcc
	v_mov_b32_e32 v241, 0
	v_lshl_add_u64 v[242:243], v[242:243], 0, v[240:241]
	global_load_dword v252, v[242:243], off
	v_add_u32_e32 v236, 0x3000, v236
